# spatial-gating phase: next group's v-tile prefetch issued after this group's W_s/u loads, waited (vmcnt(4)) before looping back; plus pipelined fragment reads
# speedup vs baseline: 1.0036x; 1.0036x over previous
; __device__ __forceinline__ unsigned pk2(float lo, float hi) { return pg8::cvt_pk_bf16(lo, hi); }
; __device__ __forceinline__ float bflo(unsigned w) { return __uint_as_float(w << 16); }
; __device__ __forceinline__ float bfhi(unsigned w) { return __uint_as_float(w & 0xffff0000u); }
; __device__ __forceinline__ void spatial_phase(KArgs A, LAS unsigned char* lds, int G) {
;     ...
;             { const f32x4 g0 = *(const f32x4*)(ln_g + g * 128 + 8 * cc), g1 = *(const f32x4*)(ln_g + g * 128 + 8 * cc + 4), b0 = *(const f32x4*)(ln_b + g * 128 + 8 * cc), b1 = *(const f32x4*)(ln_b + g * 128 + 8 * cc + 4);
; #pragma unroll
;               for (int i = 0; i < 8; ++i) { const float gg = i < 4 ? g0[i & 3] : g1[i & 3], bb = i < 4 ? b0[i & 3] : b1[i & 3];
;                   const float x0 = (i & 1) ? bfhi(r0[i >> 1]) : bflo(r0[i >> 1]), x1 = (i & 1) ? bfhi(r1[i >> 1]) : bflo(r1[i >> 1]);
;                   const float x2 = (i & 1) ? bfhi(r2[i >> 1]) : bflo(r2[i >> 1]), x3 = (i & 1) ? bfhi(r3[i >> 1]) : bflo(r3[i >> 1]);
;                   const int c = 8 * cc + i;
;                   const int swz = ((((cc & 12) | ((0 - cc) & 3))) ^ ((i & 3) << 2)) << 2;
;                   tl[c * 64 + (rp ^ swz)] = pk2((x0 - m0) * s0 * gg + bb, (x1 - m1) * s1 * gg + bb);
;                   tl[c * 64 + ((32 + rp) ^ swz)] = pk2((x2 - m2) * s2 * gg + bb, (x3 - m3) * s3 * gg + bb); } }
;             if (g < 7) { const bf16* vp = vp0 + (g + 1) * 128; r0 = *(const v4u*)vp; r1 = *(const v4u*)(vp + 2048); r2 = *(const v4u*)(vp + 64 * 2048); r3 = *(const v4u*)(vp + 65 * 2048); }
.LBB0_392:
	global_load_dwordx4 v[18:21], v[70:71], off
	global_load_dwordx4 v[26:29], v[70:71], off offset:-16
	global_load_dwordx4 v[22:25], v[68:69], off
	global_load_dwordx4 v[30:33], v[68:69], off offset:-16
	v_lshlrev_b32_e32 v35, 16, v6
	s_and_b32 s27, s7, 0x2000
	v_lshlrev_b32_e32 v34, 16, v2
	v_sub_f32_e32 v35, v35, v98
	s_lshl_b32 s27, s27, 2
	v_lshlrev_b32_e32 v36, 16, v10
	v_lshlrev_b32_e32 v37, 16, v14
	v_sub_f32_e32 v34, v34, v97
	v_mul_f32_e32 v35, v102, v35
	s_add_i32 s27, s27, 0
	v_mul_f32_e32 v34, v101, v34
	v_sub_f32_e32 v36, v36, v99
	v_sub_f32_e32 v37, v37, v100
	v_mul_f32_e32 v36, v103, v36
	v_mul_f32_e32 v37, v104, v37
	s_cmpk_eq_i32 s20, 0x700
	s_waitcnt vmcnt(0)
	v_fma_f32 v35, v26, v35, v30
	v_fma_f32 v34, v34, v26, v30
	v_cvt_pk_bf16_f32 v38, v34, v35
	v_add_u32_e32 v35, s27, v73
	v_lshl_add_u32 v34, v72, 2, v35
	v_fma_f32 v36, v26, v36, v30
	v_fma_f32 v26, v26, v37, v30
	ds_write_b32 v34, v38
	v_cvt_pk_bf16_f32 v30, v36, v26
	v_lshl_add_u32 v26, v74, 2, v35
	ds_write_b32 v26, v30
	v_and_b32_e32 v30, 0xffff0000, v2
	v_and_b32_e32 v36, 0xffff0000, v6
	v_sub_f32_e32 v30, v30, v97
	v_sub_f32_e32 v36, v36, v98
	v_mul_f32_e32 v30, v101, v30
	v_mul_f32_e32 v36, v102, v36
	v_fma_f32 v30, v30, v27, v31
	v_fma_f32 v36, v27, v36, v31
	v_and_b32_e32 v37, 0xffff0000, v10
	v_and_b32_e32 v38, 0xffff0000, v14
	v_cvt_pk_bf16_f32 v36, v30, v36
	v_lshl_add_u32 v30, v75, 2, v35
	ds_write_b32 v30, v36 offset:256
	v_sub_f32_e32 v36, v37, v99
	v_sub_f32_e32 v37, v38, v100
	v_mul_f32_e32 v36, v103, v36
	v_mul_f32_e32 v37, v104, v37
	v_fma_f32 v36, v27, v36, v31
	v_fma_f32 v27, v27, v37, v31
	v_cvt_pk_bf16_f32 v31, v36, v27
	v_lshl_add_u32 v27, v76, 2, v35
	ds_write_b32 v27, v31 offset:256
	v_lshlrev_b32_e32 v31, 16, v3
	v_lshlrev_b32_e32 v36, 16, v7
	v_sub_f32_e32 v31, v31, v97
	v_sub_f32_e32 v36, v36, v98
	v_mul_f32_e32 v31, v101, v31
	v_mul_f32_e32 v36, v102, v36
	v_fma_f32 v31, v31, v28, v32
	v_fma_f32 v36, v28, v36, v32
	v_lshlrev_b32_e32 v37, 16, v11
	v_lshlrev_b32_e32 v38, 16, v15
	v_cvt_pk_bf16_f32 v31, v31, v36
	v_lshl_add_u32 v36, v77, 2, v35
	ds_write_b32 v36, v31 offset:512
	v_sub_f32_e32 v31, v37, v99
	v_sub_f32_e32 v37, v38, v100
	v_mul_f32_e32 v31, v103, v31
	v_mul_f32_e32 v37, v104, v37
	v_fma_f32 v31, v28, v31, v32
	v_fma_f32 v28, v28, v37, v32
	v_cvt_pk_bf16_f32 v28, v31, v28
	v_lshl_add_u32 v31, v78, 2, v35
	ds_write_b32 v31, v28 offset:512
	v_and_b32_e32 v28, 0xffff0000, v3
	v_and_b32_e32 v32, 0xffff0000, v7
	v_sub_f32_e32 v28, v28, v97
	v_sub_f32_e32 v32, v32, v98
	v_mul_f32_e32 v28, v101, v28
	v_mul_f32_e32 v32, v102, v32
	v_fma_f32 v28, v28, v29, v33
	v_fma_f32 v32, v29, v32, v33
	v_and_b32_e32 v37, 0xffff0000, v11
	v_cvt_pk_bf16_f32 v28, v28, v32
	v_lshl_add_u32 v32, v79, 2, v35
	v_and_b32_e32 v38, 0xffff0000, v15
	ds_write_b32 v32, v28 offset:768
	v_sub_f32_e32 v28, v37, v99
	v_mul_f32_e32 v28, v103, v28
	v_sub_f32_e32 v37, v38, v100
	v_fma_f32 v28, v29, v28, v33
	v_mul_f32_e32 v37, v104, v37
	v_fmac_f32_e32 v33, v29, v37
	v_cvt_pk_bf16_f32 v28, v28, v33
	v_lshl_add_u32 v29, v80, 2, v35
	ds_write_b32 v29, v28 offset:768
	v_lshlrev_b32_e32 v28, 16, v4
	v_lshlrev_b32_e32 v33, 16, v8
	v_sub_f32_e32 v28, v28, v97
	v_mul_f32_e32 v28, v101, v28
	v_sub_f32_e32 v33, v33, v98
	v_fma_f32 v28, v28, v18, v22
	v_mul_f32_e32 v33, v102, v33
	v_lshlrev_b32_e32 v35, 16, v12
	v_lshlrev_b32_e32 v37, 16, v16
	v_fma_f32 v33, v33, v18, v22
	v_cvt_pk_bf16_f32 v28, v28, v33
	ds_write_b32 v34, v28 offset:1024
	v_sub_f32_e32 v28, v35, v99
	v_sub_f32_e32 v33, v37, v100
	v_mul_f32_e32 v28, v103, v28
	v_mul_f32_e32 v33, v104, v33
	v_fma_f32 v28, v18, v28, v22
	v_fma_f32 v18, v18, v33, v22
	v_cvt_pk_bf16_f32 v18, v28, v18
	ds_write_b32 v26, v18 offset:1024
	v_and_b32_e32 v18, 0xffff0000, v4
	v_and_b32_e32 v22, 0xffff0000, v8
	v_sub_f32_e32 v18, v18, v97
	v_mul_f32_e32 v18, v101, v18
	v_sub_f32_e32 v22, v22, v98
	v_fma_f32 v18, v18, v19, v23
	v_mul_f32_e32 v22, v102, v22
	v_and_b32_e32 v26, 0xffff0000, v12
	v_fma_f32 v22, v22, v19, v23
	v_cvt_pk_bf16_f32 v18, v18, v22
	v_and_b32_e32 v28, 0xffff0000, v16
	ds_write_b32 v30, v18 offset:1280
	v_sub_f32_e32 v18, v26, v99
	v_mul_f32_e32 v18, v103, v18
	v_sub_f32_e32 v22, v28, v100
	v_fma_f32 v18, v19, v18, v23
	v_mul_f32_e32 v22, v104, v22
	v_fma_f32 v19, v19, v22, v23
	v_cvt_pk_bf16_f32 v18, v18, v19
	ds_write_b32 v27, v18 offset:1280
	v_lshlrev_b32_e32 v18, 16, v5
	v_lshlrev_b32_e32 v19, 16, v9
	v_sub_f32_e32 v18, v18, v97
	v_mul_f32_e32 v18, v101, v18
	v_sub_f32_e32 v19, v19, v98
	v_fma_f32 v18, v18, v20, v24
	v_mul_f32_e32 v19, v102, v19
	v_lshlrev_b32_e32 v22, 16, v13
	v_fma_f32 v19, v19, v20, v24
	v_cvt_pk_bf16_f32 v18, v18, v19
	v_lshlrev_b32_e32 v23, 16, v17
	ds_write_b32 v36, v18 offset:1536
	v_sub_f32_e32 v18, v22, v99
	v_mul_f32_e32 v18, v103, v18
	v_sub_f32_e32 v19, v23, v100
	v_fma_f32 v18, v20, v18, v24
	v_mul_f32_e32 v19, v104, v19
	v_fma_f32 v19, v20, v19, v24
	v_cvt_pk_bf16_f32 v18, v18, v19
	ds_write_b32 v31, v18 offset:1536
	v_and_b32_e32 v18, 0xffff0000, v5
	v_and_b32_e32 v19, 0xffff0000, v9
	v_sub_f32_e32 v18, v18, v97
	v_mul_f32_e32 v18, v101, v18
	v_sub_f32_e32 v19, v19, v98
	v_fma_f32 v18, v18, v21, v25
	v_mul_f32_e32 v19, v102, v19
	v_and_b32_e32 v20, 0xffff0000, v13
	v_fma_f32 v19, v19, v21, v25
	v_cvt_pk_bf16_f32 v18, v18, v19
	v_and_b32_e32 v22, 0xffff0000, v17
	ds_write_b32 v32, v18 offset:1792
	v_sub_f32_e32 v18, v20, v99
	v_mul_f32_e32 v18, v103, v18
	v_sub_f32_e32 v19, v22, v100
	v_fma_f32 v18, v21, v18, v25
	v_mul_f32_e32 v19, v104, v19
	v_fmac_f32_e32 v25, v21, v19
	v_cvt_pk_bf16_f32 v18, v18, v25
	ds_write_b32 v29, v18 offset:1792
	s_cbranch_scc1 .LBB0_391
	s_branch .Lp2_tail
; #define LAS __attribute__((address_space(3)))
; __device__ __forceinline__ void spatial_phase(KArgs A, LAS unsigned char* lds, int G) {
;     ...
;             if (g < 7) { const bf16* vp = vp0 + (g + 1) * 128; r0 = *(const v4u*)vp; r1 = *(const v4u*)(vp + 2048); r2 = *(const v4u*)(vp + 64 * 2048); r3 = *(const v4u*)(vp + 65 * 2048); }
;             const int t = wave * 16 + fr; const float bsv = b_s[g * 128 + t];
;             const bf16* wrow = WsB + (size_t)(g * 128 + t) * 128 + 8 * fq;
;             bf16x8 wf[4]; v4u uu[4];
; #pragma unroll
;             for (int ks = 0; ks < 4; ++ks) wf[ks] = *(const bf16x8*)(wrow + ks * 32);
; #pragma unroll
;             for (int P = 0; P < 4; ++P) uu[P] = *(const v4u*)(UV + (row0 + t) * 2048 + g * 128 + 32 * P + 8 * fq);
;             __syncthreads();
;             f32x4 acc[4][2];
; #pragma unroll
;             for (int P = 0; P < 4; ++P) { acc[P][0] = (f32x4){0.f, 0.f, 0.f, 0.f}; acc[P][1] = (f32x4){0.f, 0.f, 0.f, 0.f}; }
; #pragma unroll
;             for (int ks = 0; ks < 4; ++ks) {
; #pragma unroll
;                 for (int P = 0; P < 4; ++P)
; #pragma unroll
;                     for (int n = 0; n < 2; ++n) { const int c = 32 * P + 8 * (fr >> 2) + 4 * n + (fr & 3); const int dw = (ks * 16 + 4 * fq) ^ ((((((c >> 3) & 12) | ((0 - (c >> 3)) & 3))) ^ ((c & 3) << 2)) << 2);
;                         const bf16x8 vf = *(const LAS bf16x8*)(tl + c * 64 + dw);
;                         acc[P][n] = __builtin_amdgcn_mfma_f32_16x16x32_bf16(vf, wf[ks], acc[P][n], 0, 0, 0); } }
.Lp2_tail:
	s_load_dwordx2 s[42:43], s[0:1], 0x38
	v_ashrrev_i32_e32 v67, 31, v66
	v_lshl_add_u64 v[70:71], v[70:71], 0, s[40:41]
	v_lshl_add_u64 v[68:69], v[68:69], 0, s[40:41]
	s_waitcnt lgkmcnt(0)
	v_lshl_add_u64 v[18:19], v[66:67], 2, s[42:43]
	global_load_dword v105, v[18:19], off
	v_lshlrev_b64 v[18:19], 8, v[66:67]
	v_lshl_add_u64 v[18:19], v[44:45], 0, v[18:19]
	global_load_dwordx4 v[106:109], v[18:19], off
	global_load_dwordx4 v[110:113], v[18:19], off offset:64
	global_load_dwordx4 v[38:41], v[18:19], off offset:128
	global_load_dwordx4 v[34:37], v[18:19], off offset:192
	v_lshl_add_u64 v[18:19], v[64:65], 0, s[20:21]
	v_add3_u32 v67, s27, v0, v81
	global_load_dwordx4 v[30:33], v[18:19], off offset:-128
	global_load_dwordx4 v[26:29], v[18:19], off offset:-64
	global_load_dwordx4 v[22:25], v[18:19], off
	s_nop 0
	global_load_dwordx4 v[18:21], v[18:19], off offset:64
	v_lshl_add_u64 v[10:11], v[62:63], 0, s[20:21]
	v_add_co_u32_e32 v2, vcc, 0x8000000, v10
	s_nop 1
	v_addc_co_u32_e32 v3, vcc, 0, v11, vcc
	v_add_co_u32_e32 v6, vcc, 0x8001000, v10
	s_nop 1
	v_addc_co_u32_e32 v7, vcc, 0, v11, vcc
	v_add_co_u32_e32 v12, vcc, 0x8040000, v10
	global_load_dwordx4 v[2:5], v[2:3], off offset:2304
	s_nop 0
	global_load_dwordx4 v[6:9], v[6:7], off offset:2304
	v_addc_co_u32_e32 v13, vcc, 0, v11, vcc
	v_add_co_u32_e32 v14, vcc, 0x8041000, v10
	s_nop 1
	v_addc_co_u32_e32 v15, vcc, 0, v11, vcc
	global_load_dwordx4 v[10:13], v[12:13], off offset:2304
	s_nop 0
	global_load_dwordx4 v[14:17], v[14:15], off offset:2304
	s_barrier
	ds_read_b128 v[114:117], v67
	ds_read_b128 v[118:121], v67 offset:1024
	v_add3_u32 v67, s27, v82, v81
	ds_read_b128 v[122:125], v67 offset:8192
	ds_read_b128 v[126:129], v67 offset:9216
	v_add3_u32 v67, s27, v83, v81
	ds_read_b128 v[130:133], v67 offset:16384
	ds_read_b128 v[134:137], v67 offset:17408
	v_add3_u32 v67, s27, v84, v81
	ds_read_b128 v[138:141], v67 offset:24576
	ds_read_b128 v[142:145], v67 offset:25600
	v_add3_u32 v67, s27, v85, v81
	v_add_u32_e32 v66, 0x80, v66
	ds_read_b128 v[146:149], v67
	ds_read_b128 v[150:153], v67 offset:1024
	v_add3_u32 v67, s27, v86, v81
	ds_read_b128 v[154:157], v67 offset:8192
	ds_read_b128 v[158:161], v67 offset:9216
	v_add3_u32 v67, s27, v87, v81
	ds_read_b128 v[162:165], v67 offset:16384
	ds_read_b128 v[166:169], v67 offset:17408
	v_add3_u32 v67, s27, v88, v81
	ds_read_b128 v[170:173], v67 offset:24576
	ds_read_b128 v[174:177], v67 offset:25600
	v_add3_u32 v67, s27, v89, v81
	s_waitcnt vmcnt(11) lgkmcnt(15)
	v_mfma_f32_16x16x32_bf16 v[114:117], v[114:117], v[106:109], 0
	s_waitcnt lgkmcnt(14)
	v_mfma_f32_16x16x32_bf16 v[118:121], v[118:121], v[106:109], 0
	s_waitcnt lgkmcnt(13)
	v_mfma_f32_16x16x32_bf16 v[122:125], v[122:125], v[106:109], 0
	s_waitcnt lgkmcnt(12)
	v_mfma_f32_16x16x32_bf16 v[126:129], v[126:129], v[106:109], 0
	s_waitcnt lgkmcnt(11)
	v_mfma_f32_16x16x32_bf16 v[130:133], v[130:133], v[106:109], 0
	s_waitcnt lgkmcnt(10)
	v_mfma_f32_16x16x32_bf16 v[134:137], v[134:137], v[106:109], 0
	s_waitcnt lgkmcnt(9)
	v_mfma_f32_16x16x32_bf16 v[138:141], v[138:141], v[106:109], 0
	s_waitcnt lgkmcnt(8)
	v_mfma_f32_16x16x32_bf16 v[142:145], v[142:145], v[106:109], 0
	ds_read_b128 v[178:181], v67
	ds_read_b128 v[182:185], v67 offset:1024
	v_add3_u32 v67, s27, v90, v81
	ds_read_b128 v[186:189], v67 offset:8192
	ds_read_b128 v[190:193], v67 offset:9216
	v_add3_u32 v67, s27, v91, v81
	ds_read_b128 v[202:205], v67 offset:16384
	ds_read_b128 v[206:209], v67 offset:17408
	v_add3_u32 v67, s27, v92, v81
	ds_read_b128 v[210:213], v67 offset:24576
	ds_read_b128 v[214:217], v67 offset:25600
	v_add3_u32 v67, s27, v93, v81
	s_waitcnt vmcnt(10) lgkmcnt(15)
	v_mfma_f32_16x16x32_bf16 v[114:117], v[146:149], v[110:113], v[114:117]
	s_waitcnt lgkmcnt(14)
	v_mfma_f32_16x16x32_bf16 v[118:121], v[150:153], v[110:113], v[118:121]
	s_waitcnt lgkmcnt(13)
	v_mfma_f32_16x16x32_bf16 v[122:125], v[154:157], v[110:113], v[122:125]
	s_waitcnt lgkmcnt(12)
	v_mfma_f32_16x16x32_bf16 v[126:129], v[158:161], v[110:113], v[126:129]
	s_waitcnt lgkmcnt(11)
	v_mfma_f32_16x16x32_bf16 v[130:133], v[162:165], v[110:113], v[130:133]
	s_waitcnt lgkmcnt(10)
	v_mfma_f32_16x16x32_bf16 v[134:137], v[166:169], v[110:113], v[134:137]
	s_waitcnt lgkmcnt(9)
	v_mfma_f32_16x16x32_bf16 v[138:141], v[170:173], v[110:113], v[138:141]
	s_waitcnt lgkmcnt(8)
	v_mfma_f32_16x16x32_bf16 v[142:145], v[174:177], v[110:113], v[142:145]
	ds_read_b128 v[146:149], v67
	ds_read_b128 v[150:153], v67 offset:1024
	v_add3_u32 v67, s27, v94, v81
	ds_read_b128 v[154:157], v67 offset:8192
	ds_read_b128 v[158:161], v67 offset:9216
	v_add3_u32 v67, s27, v95, v81
	ds_read_b128 v[162:165], v67 offset:16384
	ds_read_b128 v[166:169], v67 offset:17408
	v_add3_u32 v67, s27, v96, v81
	ds_read_b128 v[170:173], v67 offset:24576
	ds_read_b128 v[174:177], v67 offset:25600
	s_waitcnt vmcnt(9) lgkmcnt(15)
	v_mfma_f32_16x16x32_bf16 v[114:117], v[178:181], v[38:41], v[114:117]
	s_waitcnt lgkmcnt(14)
	v_mfma_f32_16x16x32_bf16 v[118:121], v[182:185], v[38:41], v[118:121]
	s_waitcnt lgkmcnt(13)
	v_mfma_f32_16x16x32_bf16 v[122:125], v[186:189], v[38:41], v[122:125]
	s_waitcnt lgkmcnt(12)
	v_mfma_f32_16x16x32_bf16 v[126:129], v[190:193], v[38:41], v[126:129]
	s_waitcnt lgkmcnt(11)
; #define LAS __attribute__((address_space(3)))
; __device__ __forceinline__ unsigned pk2(float lo, float hi) { return pg8::cvt_pk_bf16(lo, hi); }
; __device__ __forceinline__ float bflo(unsigned w) { return __uint_as_float(w << 16); }
; __device__ __forceinline__ float bfhi(unsigned w) { return __uint_as_float(w & 0xffff0000u); }
; __device__ __forceinline__ void spatial_phase(KArgs A, LAS unsigned char* lds, int G) {
;     ...
;             for (int ks = 0; ks < 4; ++ks) {
; #pragma unroll
;                 for (int P = 0; P < 4; ++P)
; #pragma unroll
;                     for (int n = 0; n < 2; ++n) { const int c = 32 * P + 8 * (fr >> 2) + 4 * n + (fr & 3); const int dw = (ks * 16 + 4 * fq) ^ ((((((c >> 3) & 12) | ((0 - (c >> 3)) & 3))) ^ ((c & 3) << 2)) << 2);
;                         const bf16x8 vf = *(const LAS bf16x8*)(tl + c * 64 + dw);
;                         acc[P][n] = __builtin_amdgcn_mfma_f32_16x16x32_bf16(vf, wf[ks], acc[P][n], 0, 0, 0); } }
; #pragma unroll
;             for (int P = 0; P < 4; ++P) { const int c0 = g * 128 + 32 * P + 8 * fq; const v4u u4 = uu[P];
;                 v4u o; o.x = pk2(bflo(u4.x) * (acc[P][0][0] + bsv), bfhi(u4.x) * (acc[P][0][1] + bsv)); o.y = pk2(bflo(u4.y) * (acc[P][0][2] + bsv), bfhi(u4.y) * (acc[P][0][3] + bsv));
;                 o.z = pk2(bflo(u4.z) * (acc[P][1][0] + bsv), bfhi(u4.z) * (acc[P][1][1] + bsv)); o.w = pk2(bflo(u4.w) * (acc[P][1][2] + bsv), bfhi(u4.w) * (acc[P][1][3] + bsv));
;                 *(v4u*)(GT + (row0 + t) * D + c0) = o; }
	v_mfma_f32_16x16x32_bf16 v[130:133], v[202:205], v[38:41], v[130:133]
	s_waitcnt lgkmcnt(10)
	v_mfma_f32_16x16x32_bf16 v[134:137], v[206:209], v[38:41], v[134:137]
	s_waitcnt lgkmcnt(9)
	v_mfma_f32_16x16x32_bf16 v[138:141], v[210:213], v[38:41], v[138:141]
	s_waitcnt lgkmcnt(8)
	v_mfma_f32_16x16x32_bf16 v[142:145], v[214:217], v[38:41], v[142:145]
	s_waitcnt vmcnt(8) lgkmcnt(7)
	v_mfma_f32_16x16x32_bf16 v[114:117], v[146:149], v[34:37], v[114:117]
	s_waitcnt lgkmcnt(6)
	v_mfma_f32_16x16x32_bf16 v[118:121], v[150:153], v[34:37], v[118:121]
	s_waitcnt lgkmcnt(5)
	v_mfma_f32_16x16x32_bf16 v[122:125], v[154:157], v[34:37], v[122:125]
	s_waitcnt lgkmcnt(4)
	v_mfma_f32_16x16x32_bf16 v[126:129], v[158:161], v[34:37], v[126:129]
	s_waitcnt lgkmcnt(3)
	v_mfma_f32_16x16x32_bf16 v[130:133], v[162:165], v[34:37], v[130:133]
	s_waitcnt lgkmcnt(2)
	v_mfma_f32_16x16x32_bf16 v[134:137], v[166:169], v[34:37], v[134:137]
	s_waitcnt lgkmcnt(1)
	v_mfma_f32_16x16x32_bf16 v[138:141], v[170:173], v[34:37], v[138:141]
	s_waitcnt lgkmcnt(0)
	v_mfma_f32_16x16x32_bf16 v[142:145], v[174:177], v[34:37], v[142:145]
	s_waitcnt vmcnt(7)
	v_lshlrev_b32_e32 v67, 16, v30
	v_and_b32_e32 v30, 0xffff0000, v30
	s_nop 2
	v_add_f32_e32 v106, v105, v114
	v_mul_f32_e32 v67, v106, v67
	v_add_f32_e32 v106, v105, v115
	v_mul_f32_e32 v30, v106, v30
	v_cvt_pk_bf16_f32 v30, v67, v30
	v_lshlrev_b32_e32 v67, 16, v31
	v_add_f32_e32 v106, v105, v116
	v_mul_f32_e32 v67, v106, v67
	v_and_b32_e32 v31, 0xffff0000, v31
	v_add_f32_e32 v106, v105, v117
	v_mul_f32_e32 v31, v106, v31
	v_cvt_pk_bf16_f32 v31, v67, v31
	v_lshlrev_b32_e32 v67, 16, v32
	v_add_f32_e32 v106, v105, v118
	v_mul_f32_e32 v67, v106, v67
	v_and_b32_e32 v32, 0xffff0000, v32
	v_add_f32_e32 v106, v105, v119
	v_mul_f32_e32 v32, v106, v32
	v_cvt_pk_bf16_f32 v32, v67, v32
	v_lshlrev_b32_e32 v67, 16, v33
	v_add_f32_e32 v106, v105, v120
	v_mul_f32_e32 v67, v106, v67
	v_and_b32_e32 v33, 0xffff0000, v33
	v_add_f32_e32 v106, v105, v121
	v_mul_f32_e32 v33, v106, v33
	v_lshl_add_u64 v[106:107], v[60:61], 0, s[20:21]
	v_cvt_pk_bf16_f32 v33, v67, v33
	global_store_dwordx4 v[106:107], v[30:33], off offset:-128
	s_add_u32 s20, s20, 0x100
	s_addc_u32 s21, s21, 0
	s_waitcnt vmcnt(7)
	v_lshlrev_b32_e32 v30, 16, v26
	v_add_f32_e32 v31, v105, v122
	v_mul_f32_e32 v30, v31, v30
	v_and_b32_e32 v26, 0xffff0000, v26
	v_add_f32_e32 v31, v105, v123
	v_mul_f32_e32 v26, v31, v26
	v_cvt_pk_bf16_f32 v26, v30, v26
	v_lshlrev_b32_e32 v30, 16, v27
	v_add_f32_e32 v31, v105, v124
	v_mul_f32_e32 v30, v31, v30
	v_and_b32_e32 v27, 0xffff0000, v27
	v_add_f32_e32 v31, v105, v125
	v_mul_f32_e32 v27, v31, v27
	v_cvt_pk_bf16_f32 v27, v30, v27
	v_lshlrev_b32_e32 v30, 16, v28
	v_add_f32_e32 v31, v105, v126
	v_mul_f32_e32 v30, v31, v30
	v_and_b32_e32 v28, 0xffff0000, v28
	v_add_f32_e32 v31, v105, v127
	v_mul_f32_e32 v28, v31, v28
	v_cvt_pk_bf16_f32 v28, v30, v28
	v_lshlrev_b32_e32 v30, 16, v29
	v_add_f32_e32 v31, v105, v128
	v_mul_f32_e32 v30, v31, v30
	v_and_b32_e32 v29, 0xffff0000, v29
	v_add_f32_e32 v31, v105, v129
	v_mul_f32_e32 v29, v31, v29
	v_cvt_pk_bf16_f32 v29, v30, v29
	global_store_dwordx4 v[106:107], v[26:29], off offset:-64
	s_addk_i32 s7, 0x2000
	s_cmpk_eq_i32 s20, 0x800
	s_waitcnt vmcnt(7)
	v_lshlrev_b32_e32 v26, 16, v22
	v_add_f32_e32 v27, v105, v130
	v_mul_f32_e32 v26, v27, v26
	v_and_b32_e32 v22, 0xffff0000, v22
	v_add_f32_e32 v27, v105, v131
	v_mul_f32_e32 v22, v27, v22
	v_cvt_pk_bf16_f32 v22, v26, v22
	v_lshlrev_b32_e32 v26, 16, v23
	v_add_f32_e32 v27, v105, v132
	v_mul_f32_e32 v26, v27, v26
	v_and_b32_e32 v23, 0xffff0000, v23
	v_add_f32_e32 v27, v105, v133
	v_mul_f32_e32 v23, v27, v23
	v_cvt_pk_bf16_f32 v23, v26, v23
	v_lshlrev_b32_e32 v26, 16, v24
	v_add_f32_e32 v27, v105, v134
	v_mul_f32_e32 v26, v27, v26
	v_and_b32_e32 v24, 0xffff0000, v24
	v_add_f32_e32 v27, v105, v135
	v_mul_f32_e32 v24, v27, v24
	v_cvt_pk_bf16_f32 v24, v26, v24
	v_lshlrev_b32_e32 v26, 16, v25
	v_add_f32_e32 v27, v105, v136
	v_mul_f32_e32 v26, v27, v26
	v_and_b32_e32 v25, 0xffff0000, v25
	v_add_f32_e32 v27, v105, v137
	v_mul_f32_e32 v25, v27, v25
	v_cvt_pk_bf16_f32 v25, v26, v25
	global_store_dwordx4 v[106:107], v[22:25], off
	s_waitcnt vmcnt(7)
	s_nop 0
	v_lshlrev_b32_e32 v22, 16, v18
	v_add_f32_e32 v23, v105, v138
	v_mul_f32_e32 v22, v23, v22
	v_and_b32_e32 v18, 0xffff0000, v18
	v_add_f32_e32 v23, v105, v139
	v_mul_f32_e32 v18, v23, v18
	v_cvt_pk_bf16_f32 v18, v22, v18
	v_lshlrev_b32_e32 v22, 16, v19
	v_add_f32_e32 v23, v105, v140
	v_mul_f32_e32 v22, v23, v22
	v_and_b32_e32 v19, 0xffff0000, v19
	v_add_f32_e32 v23, v105, v141
	v_mul_f32_e32 v19, v23, v19
	v_cvt_pk_bf16_f32 v19, v22, v19
	v_lshlrev_b32_e32 v22, 16, v20
	v_add_f32_e32 v23, v105, v142
	v_mul_f32_e32 v22, v23, v22
	v_and_b32_e32 v20, 0xffff0000, v20
	v_add_f32_e32 v23, v105, v143
	v_mul_f32_e32 v20, v23, v20
	v_cvt_pk_bf16_f32 v20, v22, v20
	v_lshlrev_b32_e32 v22, 16, v21
	v_add_f32_e32 v23, v105, v144
	v_mul_f32_e32 v22, v23, v22
	v_and_b32_e32 v21, 0xffff0000, v21
	v_add_f32_e32 v23, v105, v145
	v_mul_f32_e32 v21, v23, v21
	v_cvt_pk_bf16_f32 v21, v22, v21
	global_store_dwordx4 v[106:107], v[18:21], off offset:64
	s_waitcnt vmcnt(4)
	s_branch .LBB0_392
